# gla_pre: low-rank projection operand loads issued in groups of 16 with counted waits instead of load-wait-MFMA x32; q/k output pieces prefetched at the head-iteration top; on top of v43
# baseline (speedup 1.0000x reference)
; #define LAS __attribute__((address_space(3)))
; __device__ __forceinline__ f32x4 mma16(bf16x8 a, bf16x8 b, f32x4 c) { return __builtin_amdgcn_mfma_f32_16x16x32_bf16(a, b, c, 0, 0, 0); }
; __device__ __forceinline__ void gla_pre_phase(LAS unsigned char* lds, const bf16_t* proj, const bf16_t* hn, const bf16_t* wlr, const float* wa2, const float* ba, bf16_t* QT, bf16_t* KT, bf16_t* KH, float* DEC, int wg, int nwg, int tid) {
;     ...
;       {
;           const int tt = wave & 3, kh = wave >> 2;
;           const bf16_t* ap = hn + (t0 + 16 * tt + fr) * DM + kh * 1024 + 8 * fq;
;           const bf16_t* bp = wlr + (size_t)fr * DM + kh * 1024 + 8 * fq;
;           f32x4 acc = (f32x4){0.f, 0.f, 0.f, 0.f};
; #pragma unroll 8
;           for (int ks = 0; ks < 32; ++ks) acc = mma16(*(const bf16x8*)(ap + 32 * ks), *(const bf16x8*)(bp + 32 * ks), acc);
;           if (kh == 1) *(LAS f32x4*)(part + (tt * 64 + lane) * 4) = acc;
.LBB0_659:
	v_mov_b32_e32 v2, 0
	s_mov_b64 s[62:63], 0
	v_mov_b32_e32 v3, v2
	v_mov_b32_e32 v4, v2
	v_mov_b32_e32 v5, v2
	global_load_dwordx4 v[198:201], v[26:27], off offset:-256
	global_load_dwordx4 v[202:205], v[24:25], off offset:-256
	global_load_dwordx4 v[206:209], v[26:27], off offset:-192
	global_load_dwordx4 v[210:213], v[24:25], off offset:-192
	global_load_dwordx4 v[214:217], v[26:27], off offset:-128
	global_load_dwordx4 v[218:221], v[24:25], off offset:-128
	global_load_dwordx4 v[222:225], v[26:27], off offset:-64
	global_load_dwordx4 v[226:229], v[24:25], off offset:-64
	global_load_dwordx4 v[230:233], v[26:27], off
	global_load_dwordx4 v[234:237], v[24:25], off
	global_load_dwordx4 v[238:241], v[26:27], off offset:64
	global_load_dwordx4 v[242:245], v[24:25], off offset:64
	global_load_dwordx4 v[246:249], v[26:27], off offset:128
	global_load_dwordx4 v[114:117], v[24:25], off offset:128
	global_load_dwordx4 v[118:121], v[26:27], off offset:192
	global_load_dwordx4 v[122:125], v[24:25], off offset:192
	global_load_dwordx4 v[126:129], v[26:27], off offset:256
	global_load_dwordx4 v[130:133], v[24:25], off offset:256
	global_load_dwordx4 v[134:137], v[26:27], off offset:320
	global_load_dwordx4 v[138:141], v[24:25], off offset:320
	global_load_dwordx4 v[142:145], v[26:27], off offset:384
	global_load_dwordx4 v[146:149], v[24:25], off offset:384
	global_load_dwordx4 v[150:153], v[26:27], off offset:448
	global_load_dwordx4 v[154:157], v[24:25], off offset:448
	global_load_dwordx4 v[158:161], v[26:27], off offset:512
	global_load_dwordx4 v[162:165], v[24:25], off offset:512
	global_load_dwordx4 v[28:31], v[26:27], off offset:576
	global_load_dwordx4 v[32:35], v[24:25], off offset:576
	global_load_dwordx4 v[36:39], v[26:27], off offset:640
	global_load_dwordx4 v[40:43], v[24:25], off offset:640
	global_load_dwordx4 v[44:47], v[26:27], off offset:704
	global_load_dwordx4 v[48:51], v[24:25], off offset:704
	s_waitcnt vmcnt(30)
	v_mfma_f32_16x16x32_bf16 v[2:5], v[198:201], v[202:205], v[2:5]
	s_waitcnt vmcnt(28)
	v_mfma_f32_16x16x32_bf16 v[2:5], v[206:209], v[210:213], v[2:5]
	s_waitcnt vmcnt(26)
	v_mfma_f32_16x16x32_bf16 v[2:5], v[214:217], v[218:221], v[2:5]
	s_waitcnt vmcnt(24)
	v_mfma_f32_16x16x32_bf16 v[2:5], v[222:225], v[226:229], v[2:5]
	s_waitcnt vmcnt(22)
	v_mfma_f32_16x16x32_bf16 v[2:5], v[230:233], v[234:237], v[2:5]
	s_waitcnt vmcnt(20)
	v_mfma_f32_16x16x32_bf16 v[2:5], v[238:241], v[242:245], v[2:5]
	s_waitcnt vmcnt(18)
	v_mfma_f32_16x16x32_bf16 v[2:5], v[246:249], v[114:117], v[2:5]
	s_waitcnt vmcnt(16)
	v_mfma_f32_16x16x32_bf16 v[2:5], v[118:121], v[122:125], v[2:5]
	global_load_dwordx4 v[198:201], v[26:27], off offset:768
	global_load_dwordx4 v[202:205], v[24:25], off offset:768
	global_load_dwordx4 v[206:209], v[26:27], off offset:832
	global_load_dwordx4 v[210:213], v[24:25], off offset:832
	global_load_dwordx4 v[214:217], v[26:27], off offset:896
	global_load_dwordx4 v[218:221], v[24:25], off offset:896
	global_load_dwordx4 v[222:225], v[26:27], off offset:960
	global_load_dwordx4 v[226:229], v[24:25], off offset:960
	global_load_dwordx4 v[230:233], v[26:27], off offset:1024
	global_load_dwordx4 v[234:237], v[24:25], off offset:1024
	global_load_dwordx4 v[238:241], v[26:27], off offset:1088
	global_load_dwordx4 v[242:245], v[24:25], off offset:1088
	global_load_dwordx4 v[246:249], v[26:27], off offset:1152
	global_load_dwordx4 v[114:117], v[24:25], off offset:1152
	global_load_dwordx4 v[118:121], v[26:27], off offset:1216
	global_load_dwordx4 v[122:125], v[24:25], off offset:1216
	s_waitcnt vmcnt(30)
	v_mfma_f32_16x16x32_bf16 v[2:5], v[126:129], v[130:133], v[2:5]
	s_waitcnt vmcnt(28)
	v_mfma_f32_16x16x32_bf16 v[2:5], v[134:137], v[138:141], v[2:5]
	s_waitcnt vmcnt(26)
	v_mfma_f32_16x16x32_bf16 v[2:5], v[142:145], v[146:149], v[2:5]
	s_waitcnt vmcnt(24)
	v_mfma_f32_16x16x32_bf16 v[2:5], v[150:153], v[154:157], v[2:5]
	s_waitcnt vmcnt(22)
	v_mfma_f32_16x16x32_bf16 v[2:5], v[158:161], v[162:165], v[2:5]
	s_waitcnt vmcnt(20)
	v_mfma_f32_16x16x32_bf16 v[2:5], v[28:31], v[32:35], v[2:5]
	s_waitcnt vmcnt(18)
	v_mfma_f32_16x16x32_bf16 v[2:5], v[36:39], v[40:43], v[2:5]
	s_waitcnt vmcnt(16)
	v_mfma_f32_16x16x32_bf16 v[2:5], v[44:47], v[48:51], v[2:5]
	global_load_dwordx4 v[126:129], v[26:27], off offset:1280
	global_load_dwordx4 v[130:133], v[24:25], off offset:1280
	global_load_dwordx4 v[134:137], v[26:27], off offset:1344
	global_load_dwordx4 v[138:141], v[24:25], off offset:1344
	global_load_dwordx4 v[142:145], v[26:27], off offset:1408
	global_load_dwordx4 v[146:149], v[24:25], off offset:1408
	global_load_dwordx4 v[150:153], v[26:27], off offset:1472
	global_load_dwordx4 v[154:157], v[24:25], off offset:1472
	global_load_dwordx4 v[158:161], v[26:27], off offset:1536
	global_load_dwordx4 v[162:165], v[24:25], off offset:1536
	global_load_dwordx4 v[28:31], v[26:27], off offset:1600
	global_load_dwordx4 v[32:35], v[24:25], off offset:1600
	global_load_dwordx4 v[36:39], v[26:27], off offset:1664
	global_load_dwordx4 v[40:43], v[24:25], off offset:1664
	global_load_dwordx4 v[44:47], v[26:27], off offset:1728
	global_load_dwordx4 v[48:51], v[24:25], off offset:1728
	s_waitcnt vmcnt(30)
	v_mfma_f32_16x16x32_bf16 v[2:5], v[198:201], v[202:205], v[2:5]
	s_waitcnt vmcnt(28)
	v_mfma_f32_16x16x32_bf16 v[2:5], v[206:209], v[210:213], v[2:5]
	s_waitcnt vmcnt(26)
	v_mfma_f32_16x16x32_bf16 v[2:5], v[214:217], v[218:221], v[2:5]
	s_waitcnt vmcnt(24)
	v_mfma_f32_16x16x32_bf16 v[2:5], v[222:225], v[226:229], v[2:5]
	s_waitcnt vmcnt(22)
	v_mfma_f32_16x16x32_bf16 v[2:5], v[230:233], v[234:237], v[2:5]
	s_waitcnt vmcnt(20)
	v_mfma_f32_16x16x32_bf16 v[2:5], v[238:241], v[242:245], v[2:5]
	s_waitcnt vmcnt(18)
	v_mfma_f32_16x16x32_bf16 v[2:5], v[246:249], v[114:117], v[2:5]
	s_waitcnt vmcnt(16)
	v_mfma_f32_16x16x32_bf16 v[2:5], v[118:121], v[122:125], v[2:5]
	s_waitcnt vmcnt(14)
	v_mfma_f32_16x16x32_bf16 v[2:5], v[126:129], v[130:133], v[2:5]
	s_waitcnt vmcnt(12)
	v_mfma_f32_16x16x32_bf16 v[2:5], v[134:137], v[138:141], v[2:5]
	s_waitcnt vmcnt(10)
	v_mfma_f32_16x16x32_bf16 v[2:5], v[142:145], v[146:149], v[2:5]
	s_waitcnt vmcnt(8)
	v_mfma_f32_16x16x32_bf16 v[2:5], v[150:153], v[154:157], v[2:5]
	s_waitcnt vmcnt(6)
	v_mfma_f32_16x16x32_bf16 v[2:5], v[158:161], v[162:165], v[2:5]
	s_waitcnt vmcnt(4)
	v_mfma_f32_16x16x32_bf16 v[2:5], v[28:31], v[32:35], v[2:5]
	s_waitcnt vmcnt(2)
	v_mfma_f32_16x16x32_bf16 v[2:5], v[36:39], v[40:43], v[2:5]
	s_waitcnt vmcnt(0)
	v_mfma_f32_16x16x32_bf16 v[2:5], v[44:47], v[48:51], v[2:5]
	s_mov_b64 s[62:63], 0x800
	s_nop 1
	s_and_b64 vcc, exec, s[54:55]
	s_cbranch_vccz .LBB0_663
	s_nop 4
	ds_write_b128 v68, v[2:5] offset:6144

; __device__ __forceinline__ unsigned cvtpk(float lo, float hi) { return pg8::cvt_pk_bf16(lo, hi); }
; __device__ __forceinline__ float bflo(unsigned u) { return __uint_as_float(u << 16); }
; __device__ __forceinline__ float bfhi(unsigned u) { return __uint_as_float(u & 0xffff0000u); }
; __device__ __forceinline__ void gla_pre_phase(LAS unsigned char* lds, const bf16_t* proj, const bf16_t* hn, const bf16_t* wlr, const float* wa2, const float* ba, bf16_t* QT, bf16_t* KT, bf16_t* KH, float* DEC, int wg, int nwg, int tid) {
;     ...
;       for (int h = 0; h < GLA_H; ++h) {
;         float w[16];
; #pragma unroll
;         for (int r = 0; r < 16; ++r) w[r] = wa2[r * GLA_DK + h * 256 + d];
;         const float bias = ba[h * 256 + d];
;     ...
;         for (int i = 0; i < 4; ++i) { const int id = tid + 512 * i, t = id >> 5, dg = (id & 31) * 8;
;             const size_t row = t0 + t;
;             const u32x4 qv = *(const u32x4*)(proj + row * GLA_PP + h * 256 + dg), kv = *(const u32x4*)(proj + row * GLA_PP + 1024 + h * 256 + dg);
;             u32x4 oq, oh;
; #pragma unroll
;             for (int e = 0; e < 4; ++e) {
;                 float b0 = bbL[t * BP + dg + 2 * e], b1 = bbL[t * BP + dg + 2 * e + 1];
;                 if (t >= 32) { b0 += tot[dg + 2 * e]; b1 += tot[dg + 2 * e + 1]; }
;                 const float l0 = bl[dg + 2 * e], l1 = bl[dg + 2 * e + 1];
;                 const float q0 = bflo(qv[e]), q1 = bfhi(qv[e]), k0 = bflo(kv[e]), k1 = bfhi(kv[e]);
;                 oq[e] = cvtpk(q0 * __expf(b0) * (1.0f / 16.0f), q1 * __expf(b1) * (1.0f / 16.0f));
;                 oh[e] = cvtpk(k0 * __expf(l0 - b0), k1 * __expf(l1 - b1)); }
;             const size_t oidx = row * GLA_DK + h * 256 + dg;
;             *(u32x4*)(QT + oidx) = oq; *(u32x4*)(KH + oidx) = oh; }
;         __syncthreads();
.LBB0_666:
	s_or_b64 exec, exec, s[62:63]
	s_waitcnt lgkmcnt(3)
	v_mul_f32_e32 v0, 0x3fb8aa3b, v62
	v_exp_f32_e32 v76, v0
	v_mul_f32_e32 v0, 0x3fb8aa3b, v63
	v_exp_f32_e32 v77, v0
	v_sub_f32_e32 v0, v52, v62
	v_mul_f32_e32 v0, 0x3fb8aa3b, v0
	v_exp_f32_e32 v52, v0
	v_sub_f32_e32 v0, v53, v63
	v_mul_f32_e32 v0, 0x3fb8aa3b, v0
	v_exp_f32_e32 v53, v0
	v_lshlrev_b32_e32 v62, 16, v2
	v_and_b32_e32 v63, 0xffff0000, v2
	s_waitcnt lgkmcnt(2)
	v_mul_f32_e32 v0, 0x3fb8aa3b, v60
	v_pk_mul_f32 v[52:53], v[52:53], v[62:63]
	v_exp_f32_e32 v62, v0
	v_mul_f32_e32 v0, 0x3fb8aa3b, v61
	v_exp_f32_e32 v63, v0
	v_sub_f32_e32 v0, v50, v60
	v_mul_f32_e32 v0, 0x3fb8aa3b, v0
	v_exp_f32_e32 v50, v0
	v_sub_f32_e32 v0, v51, v61
	v_mul_f32_e32 v0, 0x3fb8aa3b, v0
	v_cvt_pk_bf16_f32 v2, v52, v53
	v_lshlrev_b32_e32 v52, 16, v7
	v_and_b32_e32 v53, 0xffff0000, v7
	v_exp_f32_e32 v51, v0
	v_pk_mul_f32 v[52:53], v[62:63], v[52:53]
	s_waitcnt lgkmcnt(1)
	v_mul_f32_e32 v0, 0x3fb8aa3b, v58
	v_pk_mul_f32 v[52:53], v[52:53], s[10:11] op_sel_hi:[1,0]
	v_lshlrev_b32_e32 v78, 16, v6
	v_cvt_pk_bf16_f32 v7, v52, v53
	v_lshlrev_b32_e32 v52, 16, v3
	v_and_b32_e32 v53, 0xffff0000, v3
	v_pk_mul_f32 v[50:51], v[50:51], v[52:53]
	v_exp_f32_e32 v52, v0
	v_mul_f32_e32 v0, 0x3fb8aa3b, v59
	v_exp_f32_e32 v53, v0
	v_sub_f32_e32 v0, v48, v58
	v_mul_f32_e32 v0, 0x3fb8aa3b, v0
	v_exp_f32_e32 v48, v0
	v_sub_f32_e32 v0, v49, v59
	v_mul_f32_e32 v0, 0x3fb8aa3b, v0
	v_cvt_pk_bf16_f32 v3, v50, v51
	v_lshlrev_b32_e32 v50, 16, v8
	v_and_b32_e32 v51, 0xffff0000, v8
	v_exp_f32_e32 v49, v0
	v_pk_mul_f32 v[50:51], v[52:53], v[50:51]
	s_waitcnt lgkmcnt(0)
	v_mul_f32_e32 v0, 0x3fb8aa3b, v56
	v_pk_mul_f32 v[50:51], v[50:51], s[10:11] op_sel_hi:[1,0]
	v_and_b32_e32 v79, 0xffff0000, v6
	v_cvt_pk_bf16_f32 v8, v50, v51
	v_lshlrev_b32_e32 v50, 16, v4
	v_and_b32_e32 v51, 0xffff0000, v4
	v_pk_mul_f32 v[48:49], v[48:49], v[50:51]
	v_exp_f32_e32 v50, v0
	v_mul_f32_e32 v0, 0x3fb8aa3b, v57
	v_exp_f32_e32 v51, v0
	v_sub_f32_e32 v0, v54, v56
	v_cvt_pk_bf16_f32 v4, v48, v49
	v_lshlrev_b32_e32 v48, 16, v9
	v_and_b32_e32 v49, 0xffff0000, v9
	v_mul_f32_e32 v0, 0x3fb8aa3b, v0
	v_pk_mul_f32 v[48:49], v[50:51], v[48:49]
	v_exp_f32_e32 v50, v0
	v_sub_f32_e32 v0, v55, v57
	v_mul_f32_e32 v0, 0x3fb8aa3b, v0
	v_exp_f32_e32 v51, v0
	v_pk_mul_f32 v[48:49], v[48:49], s[10:11] op_sel_hi:[1,0]
	v_pk_mul_f32 v[76:77], v[76:77], v[78:79]
	v_cvt_pk_bf16_f32 v9, v48, v49
	v_lshlrev_b32_e32 v48, 16, v5
	v_and_b32_e32 v49, 0xffff0000, v5
	v_lshl_add_u64 v[46:47], v[46:47], 0, v[44:45]
	v_pk_mul_f32 v[76:77], v[76:77], s[10:11] op_sel_hi:[1,0]
	v_pk_mul_f32 v[48:49], v[50:51], v[48:49]
	v_lshlrev_b64 v[46:47], 1, v[46:47]
	v_cvt_pk_bf16_f32 v6, v76, v77
	v_cvt_pk_bf16_f32 v5, v48, v49
	v_lshl_add_u64 v[48:49], s[82:83], 0, v[46:47]
	s_add_i32 s34, s34, 1
	global_store_dwordx4 v[48:49], v[6:9], off
	s_cmp_eq_u32 s34, 4
	s_nop 0
	v_lshl_add_u64 v[6:7], s[84:85], 0, v[46:47]
	global_store_dwordx4 v[6:7], v[2:5], off
	s_barrier
	s_cbranch_scc1 .LBB0_658
.LBB0_667:
	s_lshl_b32 s6, s34, 8
	s_lshl_b32 s100, s6, 1
	s_mov_b32 s101, 0
	v_lshl_add_u64 v[230:231], v[30:31], 0, s[100:101]
	global_load_dwordx4 v[198:201], v[230:231], off
	global_load_dwordx4 v[202:205], v[230:231], off offset:2048
	v_lshl_add_u64 v[230:231], v[34:35], 0, s[100:101]
	global_load_dwordx4 v[206:209], v[230:231], off
	global_load_dwordx4 v[210:213], v[230:231], off offset:2048
	v_lshl_add_u64 v[230:231], v[38:39], 0, s[100:101]
	global_load_dwordx4 v[214:217], v[230:231], off
	global_load_dwordx4 v[218:221], v[230:231], off offset:2048
	v_lshl_add_u64 v[230:231], v[42:43], 0, s[100:101]
	global_load_dwordx4 v[222:225], v[230:231], off
	global_load_dwordx4 v[226:229], v[230:231], off offset:2048
	v_or_b32_sdwa v0, s6, v11 dst_sel:DWORD dst_unused:UNUSED_PAD src0_sel:DWORD src1_sel:BYTE_0
	v_lshlrev_b64 v[54:55], 2, v[0:1]
	v_lshl_add_u64 v[56:57], s[0:1], 0, v[54:55]
	v_add_co_u32_e32 v4, vcc, 0x1000, v56
	global_load_dword v2, v[56:57], off
	s_nop 0
	v_addc_co_u32_e32 v5, vcc, 0, v57, vcc
	v_add_co_u32_e32 v6, vcc, 0x2000, v56
	global_load_dword v4, v[4:5], off
	s_nop 0
	v_addc_co_u32_e32 v7, vcc, 0, v57, vcc
	v_add_co_u32_e32 v8, vcc, 0x3000, v56
	global_load_dword v6, v[6:7], off
	s_nop 0
	v_addc_co_u32_e32 v9, vcc, 0, v57, vcc
	v_add_co_u32_e32 v46, vcc, 0x4000, v56
	global_load_dword v8, v[8:9], off
	s_nop 0
	v_addc_co_u32_e32 v47, vcc, 0, v57, vcc
	global_load_dword v3, v[46:47], off
	v_add_co_u32_e32 v46, vcc, 0x5000, v56
	v_lshl_add_u64 v[54:55], s[20:21], 0, v[54:55]
	s_nop 0
	v_addc_co_u32_e32 v47, vcc, 0, v57, vcc
	global_load_dword v5, v[46:47], off
	v_add_co_u32_e32 v46, vcc, 0x6000, v56
	global_load_dword v54, v[54:55], off
	s_nop 0
	v_addc_co_u32_e32 v47, vcc, 0, v57, vcc
	global_load_dword v7, v[46:47], off
	v_add_co_u32_e32 v46, vcc, 0x7000, v56
	v_mov_b32_e32 v0, 0
	s_nop 0
	v_addc_co_u32_e32 v47, vcc, 0, v57, vcc
	global_load_dword v9, v[46:47], off
	v_add_co_u32_e32 v46, vcc, 0x8000, v56
	s_mov_b32 s33, 0
	s_nop 0
	v_addc_co_u32_e32 v47, vcc, 0, v57, vcc
	v_add_co_u32_e32 v48, vcc, 0x9000, v56
	global_load_dword v46, v[46:47], off
	s_nop 0
	v_addc_co_u32_e32 v49, vcc, 0, v57, vcc
	v_add_co_u32_e32 v50, vcc, 0xa000, v56
	global_load_dword v48, v[48:49], off
	s_nop 0
	v_addc_co_u32_e32 v51, vcc, 0, v57, vcc
	v_add_co_u32_e32 v52, vcc, 0xb000, v56
	global_load_dword v50, v[50:51], off
	s_nop 0
	v_addc_co_u32_e32 v53, vcc, 0, v57, vcc
	v_add_co_u32_e32 v58, vcc, 0xc000, v56
	global_load_dword v52, v[52:53], off
	s_nop 0
	v_addc_co_u32_e32 v59, vcc, 0, v57, vcc
	global_load_dword v47, v[58:59], off
	v_add_co_u32_e32 v58, vcc, 0xd000, v56
	v_mov_b32_e32 v55, v66
	s_nop 0
	v_addc_co_u32_e32 v59, vcc, 0, v57, vcc
	global_load_dword v49, v[58:59], off
	v_add_co_u32_e32 v58, vcc, 0xe000, v56
	s_nop 1
	v_addc_co_u32_e32 v59, vcc, 0, v57, vcc
	v_add_co_u32_e32 v56, vcc, 0xf000, v56
	global_load_dword v51, v[58:59], off
	s_nop 0
	v_addc_co_u32_e32 v57, vcc, 0, v57, vcc
	global_load_dword v53, v[56:57], off
	s_barrier

; __device__ __forceinline__ void gla_pre_phase(LAS unsigned char* lds, const bf16_t* proj, const bf16_t* hn, const bf16_t* wlr, const float* wa2, const float* ba, bf16_t* QT, bf16_t* KT, bf16_t* KH, float* DEC, int wg, int nwg, int tid) {
;     ...
;         for (int i = 0; i < 4; ++i) { const int id = tid + 512 * i, t = id >> 5, dg = (id & 31) * 8;
;             const size_t row = t0 + t;
;             const u32x4 qv = *(const u32x4*)(proj + row * GLA_PP + h * 256 + dg), kv = *(const u32x4*)(proj + row * GLA_PP + 1024 + h * 256 + dg);
;             u32x4 oq, oh;
; #pragma unroll
;             for (int e = 0; e < 4; ++e) {
;                 float b0 = bbL[t * BP + dg + 2 * e], b1 = bbL[t * BP + dg + 2 * e + 1];
;                 if (t >= 32) { b0 += tot[dg + 2 * e]; b1 += tot[dg + 2 * e + 1]; }
.LBB0_675:
	s_or_b64 exec, exec, s[62:63]
	v_lshlrev_b32_e32 v0, 1, v46
	v_lshl_add_u64 v[2:3], v[30:31], 0, v[0:1]
	s_waitcnt lgkmcnt(0)
	s_barrier
	v_mov_b64_e32 v[6:7], v[198:199]
	v_mov_b64_e32 v[8:9], v[200:201]
	v_mov_b64_e32 v[2:3], v[202:203]
	v_mov_b64_e32 v[4:5], v[204:205]
	ds_read_b64 v[60:61], v71 offset:6144
	s_and_saveexec_b64 s[62:63], s[46:47]
	s_cbranch_execz .LBB0_677
	ds_read_b64 v[48:49], v65 offset:4096
	s_waitcnt lgkmcnt(0)
	v_pk_add_f32 v[60:61], v[60:61], v[48:49]

; __device__ __forceinline__ unsigned cvtpk(float lo, float hi) { return pg8::cvt_pk_bf16(lo, hi); }
; __device__ __forceinline__ float bflo(unsigned u) { return __uint_as_float(u << 16); }
; __device__ __forceinline__ float bfhi(unsigned u) { return __uint_as_float(u & 0xffff0000u); }
; __device__ __forceinline__ void gla_pre_phase(LAS unsigned char* lds, const bf16_t* proj, const bf16_t* hn, const bf16_t* wlr, const float* wa2, const float* ba, bf16_t* QT, bf16_t* KT, bf16_t* KH, float* DEC, int wg, int nwg, int tid) {
;     ...
;             const u32x4 qv = *(const u32x4*)(proj + row * GLA_PP + h * 256 + dg), kv = *(const u32x4*)(proj + row * GLA_PP + 1024 + h * 256 + dg);
;             u32x4 oq, oh;
; #pragma unroll
;             for (int e = 0; e < 4; ++e) {
;                 float b0 = bbL[t * BP + dg + 2 * e], b1 = bbL[t * BP + dg + 2 * e + 1];
;                 if (t >= 32) { b0 += tot[dg + 2 * e]; b1 += tot[dg + 2 * e + 1]; }
;                 const float l0 = bl[dg + 2 * e], l1 = bl[dg + 2 * e + 1];
;                 const float q0 = bflo(qv[e]), q1 = bfhi(qv[e]), k0 = bflo(kv[e]), k1 = bfhi(kv[e]);
;                 oq[e] = cvtpk(q0 * __expf(b0) * (1.0f / 16.0f), q1 * __expf(b1) * (1.0f / 16.0f));
;                 oh[e] = cvtpk(k0 * __expf(l0 - b0), k1 * __expf(l1 - b1)); }
;             const size_t oidx = row * GLA_DK + h * 256 + dg;
;             *(u32x4*)(QT + oidx) = oq; *(u32x4*)(KH + oidx) = oh; }
.LBB0_683:
	s_or_b64 exec, exec, s[62:63]
	s_waitcnt lgkmcnt(6)
	v_mul_f32_e32 v62, 0x3fb8aa3b, v60
	v_mul_f32_e32 v63, 0x3fb8aa3b, v61
	v_lshlrev_b32_e32 v76, 16, v6
	v_and_b32_e32 v77, 0xffff0000, v6
	s_waitcnt lgkmcnt(5)
	v_sub_f32_e32 v6, v52, v60
	v_exp_f32_e32 v62, v62
	v_exp_f32_e32 v63, v63
	v_mul_f32_e32 v6, 0x3fb8aa3b, v6
	v_exp_f32_e32 v60, v6
	v_sub_f32_e32 v6, v53, v61
	v_mul_f32_e32 v6, 0x3fb8aa3b, v6
	v_exp_f32_e32 v61, v6
	v_pk_mul_f32 v[62:63], v[62:63], v[76:77]
	v_or_b32_e32 v46, v46, v10
	v_pk_mul_f32 v[62:63], v[62:63], s[10:11] op_sel_hi:[1,0]
	s_nop 0
	v_cvt_pk_bf16_f32 v6, v62, v63
	v_lshlrev_b32_e32 v62, 16, v2
	v_and_b32_e32 v63, 0xffff0000, v2
	s_waitcnt lgkmcnt(4)
	v_mul_f32_e32 v2, 0x3fb8aa3b, v58
	v_pk_mul_f32 v[60:61], v[60:61], v[62:63]
	v_exp_f32_e32 v62, v2
	v_mul_f32_e32 v2, 0x3fb8aa3b, v59
	v_exp_f32_e32 v63, v2
	v_cvt_pk_bf16_f32 v2, v60, v61
	v_lshlrev_b32_e32 v60, 16, v7
	v_and_b32_e32 v61, 0xffff0000, v7
	s_waitcnt lgkmcnt(3)
	v_sub_f32_e32 v7, v50, v58
	v_mul_f32_e32 v7, 0x3fb8aa3b, v7
	v_exp_f32_e32 v58, v7
	v_sub_f32_e32 v7, v51, v59
	v_mul_f32_e32 v7, 0x3fb8aa3b, v7
	v_exp_f32_e32 v59, v7
	v_pk_mul_f32 v[60:61], v[62:63], v[60:61]
	s_nop 0
	v_pk_mul_f32 v[60:61], v[60:61], s[10:11] op_sel_hi:[1,0]
	s_nop 0
	v_cvt_pk_bf16_f32 v7, v60, v61
	v_lshlrev_b32_e32 v60, 16, v3
	v_and_b32_e32 v61, 0xffff0000, v3
	s_waitcnt lgkmcnt(2)
	v_mul_f32_e32 v3, 0x3fb8aa3b, v54
	v_pk_mul_f32 v[58:59], v[58:59], v[60:61]
	v_exp_f32_e32 v60, v3
	v_mul_f32_e32 v3, 0x3fb8aa3b, v55
	v_exp_f32_e32 v61, v3
	v_cvt_pk_bf16_f32 v3, v58, v59
	v_lshlrev_b32_e32 v58, 16, v8
	v_and_b32_e32 v59, 0xffff0000, v8
	s_waitcnt lgkmcnt(1)
	v_sub_f32_e32 v8, v48, v54
	v_mul_f32_e32 v8, 0x3fb8aa3b, v8
	v_exp_f32_e32 v54, v8
	v_sub_f32_e32 v8, v49, v55
	v_mul_f32_e32 v8, 0x3fb8aa3b, v8
	v_exp_f32_e32 v55, v8
	v_pk_mul_f32 v[58:59], v[60:61], v[58:59]
	v_lshlrev_b32_e32 v60, 16, v9
	v_pk_mul_f32 v[58:59], v[58:59], s[10:11] op_sel_hi:[1,0]
	v_and_b32_e32 v61, 0xffff0000, v9
	v_cvt_pk_bf16_f32 v8, v58, v59
	v_lshlrev_b32_e32 v58, 16, v4
	v_and_b32_e32 v59, 0xffff0000, v4
	v_pk_mul_f32 v[54:55], v[54:55], v[58:59]
	s_nop 0
	v_cvt_pk_bf16_f32 v4, v54, v55
	s_waitcnt lgkmcnt(0)
	v_mul_f32_e32 v54, 0x3fb8aa3b, v56
	v_exp_f32_e32 v58, v54
	v_mul_f32_e32 v54, 0x3fb8aa3b, v57
	v_exp_f32_e32 v59, v54
	ds_read_b64 v[54:55], v65 offset:5144
	v_pk_mul_f32 v[58:59], v[58:59], v[60:61]
	s_nop 0
	v_pk_mul_f32 v[60:61], v[58:59], s[10:11] op_sel_hi:[1,0]
	ds_read_b64 v[58:59], v72 offset:6144
	s_waitcnt lgkmcnt(1)
	v_sub_f32_e32 v9, v54, v56
	v_mul_f32_e32 v9, 0x3fb8aa3b, v9
	v_exp_f32_e32 v56, v9
	v_sub_f32_e32 v9, v55, v57
	v_mul_f32_e32 v9, 0x3fb8aa3b, v9
	v_exp_f32_e32 v57, v9
	v_cvt_pk_bf16_f32 v9, v60, v61
	v_lshlrev_b32_e32 v60, 16, v5
	v_and_b32_e32 v61, 0xffff0000, v5
	v_pk_mul_f32 v[56:57], v[56:57], v[60:61]
	s_nop 0
	v_cvt_pk_bf16_f32 v5, v56, v57
	v_lshl_add_u64 v[56:57], v[46:47], 0, v[32:33]
	v_lshlrev_b64 v[56:57], 1, v[56:57]
	v_lshl_add_u64 v[60:61], s[82:83], 0, v[56:57]
	global_store_dwordx4 v[60:61], v[6:9], off
	s_nop 1
	v_lshl_add_u64 v[6:7], s[84:85], 0, v[56:57]
	global_store_dwordx4 v[6:7], v[2:5], off
	s_nop 1
	v_lshl_add_u64 v[2:3], v[34:35], 0, v[0:1]
	v_mov_b64_e32 v[6:7], v[206:207]
	v_mov_b64_e32 v[8:9], v[208:209]
	v_mov_b64_e32 v[2:3], v[210:211]
	v_mov_b64_e32 v[4:5], v[212:213]
	s_and_saveexec_b64 s[62:63], s[48:49]
	s_cbranch_execz .LBB0_687
	ds_read_b64 v[56:57], v65 offset:4096
	s_waitcnt lgkmcnt(0)
	v_pk_add_f32 v[58:59], v[58:59], v[56:57]
	s_or_b64 exec, exec, s[62:63]
	ds_read_b64 v[62:63], v72 offset:6152
	s_and_saveexec_b64 s[62:63], s[48:49]
	s_cbranch_execnz .LBB0_688

; __device__ __forceinline__ unsigned cvtpk(float lo, float hi) { return pg8::cvt_pk_bf16(lo, hi); }
; __device__ __forceinline__ float bflo(unsigned u) { return __uint_as_float(u << 16); }
; __device__ __forceinline__ float bfhi(unsigned u) { return __uint_as_float(u & 0xffff0000u); }
; __device__ __forceinline__ void gla_pre_phase(LAS unsigned char* lds, const bf16_t* proj, const bf16_t* hn, const bf16_t* wlr, const float* wa2, const float* ba, bf16_t* QT, bf16_t* KT, bf16_t* KH, float* DEC, int wg, int nwg, int tid) {
;     ...
;             const u32x4 qv = *(const u32x4*)(proj + row * GLA_PP + h * 256 + dg), kv = *(const u32x4*)(proj + row * GLA_PP + 1024 + h * 256 + dg);
;             u32x4 oq, oh;
; #pragma unroll
;             for (int e = 0; e < 4; ++e) {
;                 float b0 = bbL[t * BP + dg + 2 * e], b1 = bbL[t * BP + dg + 2 * e + 1];
;                 if (t >= 32) { b0 += tot[dg + 2 * e]; b1 += tot[dg + 2 * e + 1]; }
;                 const float l0 = bl[dg + 2 * e], l1 = bl[dg + 2 * e + 1];
;                 const float q0 = bflo(qv[e]), q1 = bfhi(qv[e]), k0 = bflo(kv[e]), k1 = bfhi(kv[e]);
;                 oq[e] = cvtpk(q0 * __expf(b0) * (1.0f / 16.0f), q1 * __expf(b1) * (1.0f / 16.0f));
;                 oh[e] = cvtpk(k0 * __expf(l0 - b0), k1 * __expf(l1 - b1)); }
;             const size_t oidx = row * GLA_DK + h * 256 + dg;
;             *(u32x4*)(QT + oidx) = oq; *(u32x4*)(KH + oidx) = oh; }
.LBB0_691:
	s_or_b64 exec, exec, s[62:63]
	s_waitcnt lgkmcnt(3)
	v_mul_f32_e32 v75, 0x3fb8aa3b, v58
	v_exp_f32_e32 v76, v75
	v_mul_f32_e32 v75, 0x3fb8aa3b, v59
	v_lshlrev_b32_e32 v78, 16, v6
	v_and_b32_e32 v79, 0xffff0000, v6
	v_sub_f32_e32 v6, v52, v58
	v_exp_f32_e32 v77, v75
	v_mul_f32_e32 v6, 0x3fb8aa3b, v6
	v_exp_f32_e32 v58, v6
	v_sub_f32_e32 v6, v53, v59
	v_mul_f32_e32 v6, 0x3fb8aa3b, v6
	v_exp_f32_e32 v59, v6
	v_pk_mul_f32 v[76:77], v[76:77], v[78:79]
	s_nop 0
	v_pk_mul_f32 v[76:77], v[76:77], s[10:11] op_sel_hi:[1,0]
	s_nop 0
	v_cvt_pk_bf16_f32 v6, v76, v77
	v_lshlrev_b32_e32 v76, 16, v2
	v_and_b32_e32 v77, 0xffff0000, v2
	s_waitcnt lgkmcnt(2)
	v_mul_f32_e32 v2, 0x3fb8aa3b, v62
	v_pk_mul_f32 v[58:59], v[58:59], v[76:77]
	v_exp_f32_e32 v76, v2
	v_mul_f32_e32 v2, 0x3fb8aa3b, v63
	v_exp_f32_e32 v77, v2
	v_cvt_pk_bf16_f32 v2, v58, v59
	v_lshlrev_b32_e32 v58, 16, v7
	v_and_b32_e32 v59, 0xffff0000, v7
	v_sub_f32_e32 v7, v50, v62
	v_mul_f32_e32 v7, 0x3fb8aa3b, v7
	v_exp_f32_e32 v62, v7
	v_sub_f32_e32 v7, v51, v63
	v_mul_f32_e32 v7, 0x3fb8aa3b, v7
	v_exp_f32_e32 v63, v7
	v_pk_mul_f32 v[58:59], v[76:77], v[58:59]
	s_nop 0
	v_pk_mul_f32 v[58:59], v[58:59], s[10:11] op_sel_hi:[1,0]
	s_nop 0
	v_cvt_pk_bf16_f32 v7, v58, v59
	v_lshlrev_b32_e32 v58, 16, v3
	v_and_b32_e32 v59, 0xffff0000, v3
	s_waitcnt lgkmcnt(1)
	v_mul_f32_e32 v3, 0x3fb8aa3b, v60
	v_pk_mul_f32 v[58:59], v[62:63], v[58:59]
	v_exp_f32_e32 v62, v3
	v_mul_f32_e32 v3, 0x3fb8aa3b, v61
	v_exp_f32_e32 v63, v3
	v_cvt_pk_bf16_f32 v3, v58, v59
	v_lshlrev_b32_e32 v58, 16, v8
	v_and_b32_e32 v59, 0xffff0000, v8
	v_sub_f32_e32 v8, v48, v60
	v_mul_f32_e32 v8, 0x3fb8aa3b, v8
	v_exp_f32_e32 v60, v8
	v_sub_f32_e32 v8, v49, v61
	v_mul_f32_e32 v8, 0x3fb8aa3b, v8
	v_exp_f32_e32 v61, v8
	v_pk_mul_f32 v[58:59], v[62:63], v[58:59]
	s_nop 0
	v_pk_mul_f32 v[58:59], v[58:59], s[10:11] op_sel_hi:[1,0]
	s_nop 0
	v_cvt_pk_bf16_f32 v8, v58, v59
	v_lshlrev_b32_e32 v58, 16, v4
	v_and_b32_e32 v59, 0xffff0000, v4
	s_waitcnt lgkmcnt(0)
	v_mul_f32_e32 v4, 0x3fb8aa3b, v56
	v_pk_mul_f32 v[58:59], v[60:61], v[58:59]
	v_exp_f32_e32 v60, v4
	v_mul_f32_e32 v4, 0x3fb8aa3b, v57
	v_exp_f32_e32 v61, v4
	v_cvt_pk_bf16_f32 v4, v58, v59
	v_lshlrev_b32_e32 v58, 16, v9
	v_and_b32_e32 v59, 0xffff0000, v9
	v_sub_f32_e32 v9, v54, v56
	v_mul_f32_e32 v9, 0x3fb8aa3b, v9
	v_exp_f32_e32 v56, v9
	v_sub_f32_e32 v9, v55, v57
	v_mul_f32_e32 v9, 0x3fb8aa3b, v9
	v_exp_f32_e32 v57, v9
	v_pk_mul_f32 v[58:59], v[60:61], v[58:59]
	s_nop 0
	v_pk_mul_f32 v[58:59], v[58:59], s[10:11] op_sel_hi:[1,0]
	s_nop 0
	v_cvt_pk_bf16_f32 v9, v58, v59
	v_lshlrev_b32_e32 v58, 16, v5
	v_and_b32_e32 v59, 0xffff0000, v5
	v_pk_mul_f32 v[56:57], v[56:57], v[58:59]
	s_nop 0
	v_cvt_pk_bf16_f32 v5, v56, v57
	v_lshl_add_u64 v[56:57], v[46:47], 0, v[36:37]
	v_lshlrev_b64 v[56:57], 1, v[56:57]
	v_lshl_add_u64 v[58:59], s[82:83], 0, v[56:57]
	global_store_dwordx4 v[58:59], v[6:9], off
	s_nop 1
	v_lshl_add_u64 v[6:7], s[84:85], 0, v[56:57]
	global_store_dwordx4 v[6:7], v[2:5], off
	s_nop 1
	v_lshl_add_u64 v[2:3], v[38:39], 0, v[0:1]
	v_mov_b64_e32 v[6:7], v[214:215]
	v_mov_b64_e32 v[8:9], v[216:217]
	v_mov_b64_e32 v[2:3], v[218:219]
	v_mov_b64_e32 v[4:5], v[220:221]
	ds_read_b64 v[62:63], v73 offset:6144
	s_and_saveexec_b64 s[62:63], s[50:51]
	s_cbranch_execz .LBB0_695
	ds_read_b64 v[56:57], v65 offset:4096
	s_waitcnt lgkmcnt(0)
	v_pk_add_f32 v[62:63], v[62:63], v[56:57]
	s_or_b64 exec, exec, s[62:63]
	ds_read_b64 v[60:61], v73 offset:6152
	s_and_saveexec_b64 s[62:63], s[50:51]
	s_cbranch_execnz .LBB0_696

; __device__ __forceinline__ unsigned cvtpk(float lo, float hi) { return pg8::cvt_pk_bf16(lo, hi); }
; __device__ __forceinline__ float bflo(unsigned u) { return __uint_as_float(u << 16); }
; __device__ __forceinline__ float bfhi(unsigned u) { return __uint_as_float(u & 0xffff0000u); }
; __device__ __forceinline__ void gla_pre_phase(LAS unsigned char* lds, const bf16_t* proj, const bf16_t* hn, const bf16_t* wlr, const float* wa2, const float* ba, bf16_t* QT, bf16_t* KT, bf16_t* KH, float* DEC, int wg, int nwg, int tid) {
;     ...
;         for (int i = 0; i < 4; ++i) { const int id = tid + 512 * i, t = id >> 5, dg = (id & 31) * 8;
;             const size_t row = t0 + t;
;             const u32x4 qv = *(const u32x4*)(proj + row * GLA_PP + h * 256 + dg), kv = *(const u32x4*)(proj + row * GLA_PP + 1024 + h * 256 + dg);
;             u32x4 oq, oh;
; #pragma unroll
;             for (int e = 0; e < 4; ++e) {
;                 float b0 = bbL[t * BP + dg + 2 * e], b1 = bbL[t * BP + dg + 2 * e + 1];
;                 if (t >= 32) { b0 += tot[dg + 2 * e]; b1 += tot[dg + 2 * e + 1]; }
;                 const float l0 = bl[dg + 2 * e], l1 = bl[dg + 2 * e + 1];
;                 const float q0 = bflo(qv[e]), q1 = bfhi(qv[e]), k0 = bflo(kv[e]), k1 = bfhi(kv[e]);
;                 oq[e] = cvtpk(q0 * __expf(b0) * (1.0f / 16.0f), q1 * __expf(b1) * (1.0f / 16.0f));
;                 oh[e] = cvtpk(k0 * __expf(l0 - b0), k1 * __expf(l1 - b1)); }
;             const size_t oidx = row * GLA_DK + h * 256 + dg;
;             *(u32x4*)(QT + oidx) = oq; *(u32x4*)(KH + oidx) = oh; }
.LBB0_699:
	s_or_b64 exec, exec, s[62:63]
	s_waitcnt lgkmcnt(3)
	v_mul_f32_e32 v75, 0x3fb8aa3b, v62
	v_exp_f32_e32 v76, v75
	v_mul_f32_e32 v75, 0x3fb8aa3b, v63
	v_lshlrev_b32_e32 v78, 16, v6
	v_and_b32_e32 v79, 0xffff0000, v6
	v_sub_f32_e32 v6, v52, v62
	v_exp_f32_e32 v77, v75
	v_mul_f32_e32 v6, 0x3fb8aa3b, v6
	v_exp_f32_e32 v62, v6
	v_sub_f32_e32 v6, v53, v63
	v_mul_f32_e32 v6, 0x3fb8aa3b, v6
	v_exp_f32_e32 v63, v6
	v_pk_mul_f32 v[76:77], v[76:77], v[78:79]
	s_nop 0
	v_pk_mul_f32 v[76:77], v[76:77], s[10:11] op_sel_hi:[1,0]
	s_nop 0
	v_cvt_pk_bf16_f32 v6, v76, v77
	v_lshlrev_b32_e32 v76, 16, v2
	v_and_b32_e32 v77, 0xffff0000, v2
	s_waitcnt lgkmcnt(2)
	v_mul_f32_e32 v2, 0x3fb8aa3b, v60
	v_pk_mul_f32 v[62:63], v[62:63], v[76:77]
	v_exp_f32_e32 v76, v2
	v_mul_f32_e32 v2, 0x3fb8aa3b, v61
	v_exp_f32_e32 v77, v2
	v_cvt_pk_bf16_f32 v2, v62, v63
	v_lshlrev_b32_e32 v62, 16, v7
	v_and_b32_e32 v63, 0xffff0000, v7
	v_sub_f32_e32 v7, v50, v60
	v_mul_f32_e32 v7, 0x3fb8aa3b, v7
	v_exp_f32_e32 v60, v7
	v_sub_f32_e32 v7, v51, v61
	v_mul_f32_e32 v7, 0x3fb8aa3b, v7
	v_exp_f32_e32 v61, v7
	v_pk_mul_f32 v[62:63], v[76:77], v[62:63]
	s_nop 0
	v_pk_mul_f32 v[62:63], v[62:63], s[10:11] op_sel_hi:[1,0]
	s_nop 0
	v_cvt_pk_bf16_f32 v7, v62, v63
	v_lshlrev_b32_e32 v62, 16, v3
	v_and_b32_e32 v63, 0xffff0000, v3
	s_waitcnt lgkmcnt(1)
	v_mul_f32_e32 v3, 0x3fb8aa3b, v58
	v_pk_mul_f32 v[60:61], v[60:61], v[62:63]
	v_exp_f32_e32 v62, v3
	v_mul_f32_e32 v3, 0x3fb8aa3b, v59
	v_exp_f32_e32 v63, v3
	v_cvt_pk_bf16_f32 v3, v60, v61
	v_lshlrev_b32_e32 v60, 16, v8
	v_and_b32_e32 v61, 0xffff0000, v8
	v_sub_f32_e32 v8, v48, v58
	v_mul_f32_e32 v8, 0x3fb8aa3b, v8
	v_exp_f32_e32 v58, v8
	v_sub_f32_e32 v8, v49, v59
	v_mul_f32_e32 v8, 0x3fb8aa3b, v8
	v_exp_f32_e32 v59, v8
	v_pk_mul_f32 v[60:61], v[62:63], v[60:61]
	s_nop 0
	v_pk_mul_f32 v[60:61], v[60:61], s[10:11] op_sel_hi:[1,0]
	s_nop 0
	v_cvt_pk_bf16_f32 v8, v60, v61
	v_lshlrev_b32_e32 v60, 16, v4
	v_and_b32_e32 v61, 0xffff0000, v4
	s_waitcnt lgkmcnt(0)
	v_mul_f32_e32 v4, 0x3fb8aa3b, v56
	v_pk_mul_f32 v[58:59], v[58:59], v[60:61]
	v_exp_f32_e32 v60, v4
	v_mul_f32_e32 v4, 0x3fb8aa3b, v57
	v_exp_f32_e32 v61, v4
	v_cvt_pk_bf16_f32 v4, v58, v59
	v_lshlrev_b32_e32 v58, 16, v9
	v_and_b32_e32 v59, 0xffff0000, v9
	v_sub_f32_e32 v9, v54, v56
	v_mul_f32_e32 v9, 0x3fb8aa3b, v9
	v_exp_f32_e32 v56, v9
	v_sub_f32_e32 v9, v55, v57
	v_mul_f32_e32 v9, 0x3fb8aa3b, v9
	v_exp_f32_e32 v57, v9
	v_pk_mul_f32 v[58:59], v[60:61], v[58:59]
	s_nop 0
	v_pk_mul_f32 v[58:59], v[58:59], s[10:11] op_sel_hi:[1,0]
	s_nop 0
	v_cvt_pk_bf16_f32 v9, v58, v59
	v_lshlrev_b32_e32 v58, 16, v5
	v_and_b32_e32 v59, 0xffff0000, v5
	v_pk_mul_f32 v[56:57], v[56:57], v[58:59]
	s_nop 0
	v_cvt_pk_bf16_f32 v5, v56, v57
	v_lshl_add_u64 v[56:57], v[46:47], 0, v[40:41]
	v_lshlrev_b64 v[56:57], 1, v[56:57]
	v_lshl_add_u64 v[58:59], s[82:83], 0, v[56:57]
	global_store_dwordx4 v[58:59], v[6:9], off
	s_nop 1
	v_lshl_add_u64 v[6:7], s[84:85], 0, v[56:57]
	global_store_dwordx4 v[6:7], v[2:5], off
	s_nop 1
	v_lshl_add_u64 v[2:3], v[42:43], 0, v[0:1]
	v_mov_b64_e32 v[6:7], v[222:223]
	v_mov_b64_e32 v[8:9], v[224:225]
	v_mov_b64_e32 v[2:3], v[226:227]
	v_mov_b64_e32 v[4:5], v[228:229]
	ds_read_b64 v[62:63], v74 offset:6144
	s_and_saveexec_b64 s[62:63], s[52:53]
	s_cbranch_execz .LBB0_703
	ds_read_b64 v[56:57], v65 offset:4096
	s_waitcnt lgkmcnt(0)
	v_pk_add_f32 v[62:63], v[62:63], v[56:57]
	s_or_b64 exec, exec, s[62:63]
	ds_read_b64 v[60:61], v74 offset:6152
	s_and_saveexec_b64 s[62:63], s[52:53]
	s_cbranch_execnz .LBB0_704
